# MLA block epilogue: DPP neighbour exchange instead of 64 serialized ds_bpermute round trips (SB epilogue unchanged)
# speedup vs baseline: 1.0031x; 1.0031x over previous
; __device__ __forceinline__ void partialSM(f32x16& p0, f32x16& p1, float& m_reg, float& mn, float& alpha) {
;     ...
;     const float mnL = -mn * C2;
;     for (int r = 0; r < 16; ++r) p0[r] = fmaf(p0[r], C2, mnL); for (int r = 0; r < 16; ++r) p1[r] = fmaf(p1[r], C2, mnL);
;     for (int r = 0; r < 16; ++r) p0[r] = __builtin_amdgcn_exp2f(p0[r]);
; }
; __device__ __forceinline__ void finishSM(f32x16& p0, f32x16& p1, float alpha, float& l_reg, bf16x8& pa0, bf16x8& pa1, bf16x8& pa2, bf16x8& pa3) {
;     for (int r = 0; r < 16; ++r) p1[r] = __builtin_amdgcn_exp2f(p1[r]);
;     float ps = 0; for (int r = 0; r < 16; ++r) ps += p0[r]; for (int r = 0; r < 16; ++r) ps += p1[r];
;     { auto rr = __builtin_amdgcn_permlane32_swap(__float_as_uint(ps), __float_as_uint(ps), false, false);
;       ps = __uint_as_float(rr[0]) + __uint_as_float(rr[1]); }
;     l_reg = l_reg * alpha + ps;
;     ...
;     PK4(p0, 0, pa0); PK4(p0, 8, pa1); PK4(p1, 0, pa2); PK4(p1, 8, pa3);
; template <int VB, bool SK>
; __device__ __forceinline__ void pv_tile(f32x16* o, int vb0, bf16x8 pa0, bf16x8 pa1, bf16x8 pa2, bf16x8 pa3, bool act) {
;     ...
;     PV_D0(0); PV_D0(1); PV_D0(2); PV_D0(3);
.LBB0_847:
	v_cndmask_b32_e64 v195, v197, v195, s[6:7]
	v_mul_f32_e32 v197, 0xbdd53b94, v195
	v_fmamk_f32 v82, v82, 0x3dd53b94, v197
	v_fmamk_f32 v83, v83, 0x3dd53b94, v197
	v_fmamk_f32 v84, v84, 0x3dd53b94, v197
	v_fmamk_f32 v85, v85, 0x3dd53b94, v197
	v_fmamk_f32 v86, v86, 0x3dd53b94, v197
	v_fmamk_f32 v87, v87, 0x3dd53b94, v197
	v_fmamk_f32 v88, v88, 0x3dd53b94, v197
	v_fmamk_f32 v89, v89, 0x3dd53b94, v197
	v_fmamk_f32 v90, v90, 0x3dd53b94, v197
	v_fmamk_f32 v91, v91, 0x3dd53b94, v197
	v_fmamk_f32 v92, v92, 0x3dd53b94, v197
	v_fmamk_f32 v93, v93, 0x3dd53b94, v197
	v_fmamk_f32 v94, v94, 0x3dd53b94, v197
	v_fmamk_f32 v95, v95, 0x3dd53b94, v197
	v_fmamk_f32 v96, v96, 0x3dd53b94, v197
	v_fmamk_f32 v97, v97, 0x3dd53b94, v197
	v_fmamk_f32 v66, v66, 0x3dd53b94, v197
	v_fmamk_f32 v67, v67, 0x3dd53b94, v197
	v_fmamk_f32 v68, v68, 0x3dd53b94, v197
	v_fmamk_f32 v69, v69, 0x3dd53b94, v197
	v_fmamk_f32 v70, v70, 0x3dd53b94, v197
	v_fmamk_f32 v71, v71, 0x3dd53b94, v197
	v_fmamk_f32 v72, v72, 0x3dd53b94, v197
	v_fmamk_f32 v73, v73, 0x3dd53b94, v197
	v_fmamk_f32 v74, v74, 0x3dd53b94, v197
	v_fmamk_f32 v75, v75, 0x3dd53b94, v197
	v_fmamk_f32 v76, v76, 0x3dd53b94, v197
	v_fmamk_f32 v77, v77, 0x3dd53b94, v197
	v_fmamk_f32 v78, v78, 0x3dd53b94, v197
	v_fmamk_f32 v79, v79, 0x3dd53b94, v197
	v_fmamk_f32 v80, v80, 0x3dd53b94, v197
	v_fmac_f32_e32 v197, 0x3dd53b94, v81
	v_exp_f32_e32 v81, v82
	v_exp_f32_e32 v82, v83
	v_exp_f32_e32 v83, v84
	v_exp_f32_e32 v84, v85
	v_exp_f32_e32 v85, v86
	v_exp_f32_e32 v86, v87
	v_exp_f32_e32 v87, v88
	v_exp_f32_e32 v88, v89
	v_exp_f32_e32 v89, v90
	v_exp_f32_e32 v90, v91
	v_exp_f32_e32 v91, v92
	v_exp_f32_e32 v92, v93
	v_exp_f32_e32 v93, v94
	v_exp_f32_e32 v94, v95
	v_exp_f32_e32 v95, v96
	v_exp_f32_e32 v96, v97
	v_exp_f32_e32 v97, v66
	v_add_f32_e32 v66, 0, v81
	v_add_f32_e32 v66, v82, v66
	v_add_f32_e32 v66, v83, v66
	v_add_f32_e32 v66, v84, v66
	v_add_f32_e32 v66, v85, v66
	v_add_f32_e32 v66, v86, v66
	v_add_f32_e32 v66, v87, v66
	v_add_f32_e32 v66, v88, v66
	v_add_f32_e32 v66, v89, v66
	v_add_f32_e32 v66, v90, v66
	v_add_f32_e32 v66, v91, v66
	v_add_f32_e32 v66, v92, v66
	v_add_f32_e32 v66, v93, v66
	v_exp_f32_e32 v198, v67
	v_add_f32_e32 v66, v94, v66
	v_exp_f32_e32 v199, v68
	v_add_f32_e32 v66, v95, v66
	v_exp_f32_e32 v200, v69
	v_add_f32_e32 v66, v96, v66
	v_exp_f32_e32 v201, v70
	v_add_f32_e32 v66, v97, v66
	v_exp_f32_e32 v202, v71
	v_add_f32_e32 v66, v198, v66
	v_exp_f32_e32 v203, v72
	v_add_f32_e32 v66, v199, v66
	v_exp_f32_e32 v204, v73
	v_add_f32_e32 v66, v200, v66
	v_exp_f32_e32 v205, v74
	v_add_f32_e32 v66, v201, v66
	v_exp_f32_e32 v206, v75
	v_add_f32_e32 v66, v202, v66
	v_exp_f32_e32 v207, v76
	v_add_f32_e32 v66, v203, v66
	v_exp_f32_e32 v208, v77
	v_add_f32_e32 v66, v204, v66
	v_exp_f32_e32 v209, v78
	v_add_f32_e32 v66, v205, v66
	v_exp_f32_e32 v210, v79
	v_add_f32_e32 v66, v206, v66
	v_exp_f32_e32 v211, v80
	v_add_f32_e32 v66, v207, v66
	v_exp_f32_e32 v197, v197
	v_add_f32_e32 v66, v208, v66
	v_add_f32_e32 v66, v209, v66
	v_add_f32_e32 v66, v210, v66
	v_add_f32_e32 v66, v211, v66
	v_add_f32_e32 v66, v197, v66
	v_mov_b32_e32 v67, v66
	s_nop 1
	v_permlane32_swap_b32_e32 v66, v67
	v_add_f32_e32 v212, v66, v67
	v_cvt_pk_bf16_f32 v66, v81, v82
	v_cvt_pk_bf16_f32 v67, v83, v84
	v_cvt_pk_bf16_f32 v68, v85, v86
	v_cvt_pk_bf16_f32 v69, v87, v88
	v_cvt_pk_bf16_f32 v70, v89, v90
	v_cvt_pk_bf16_f32 v71, v91, v92
	v_cvt_pk_bf16_f32 v72, v93, v94
	v_cvt_pk_bf16_f32 v73, v95, v96
	v_cvt_pk_bf16_f32 v74, v97, v198
	v_cvt_pk_bf16_f32 v75, v199, v200
	v_cvt_pk_bf16_f32 v76, v201, v202
	v_cvt_pk_bf16_f32 v77, v203, v204
	v_cvt_pk_bf16_f32 v78, v205, v206
	v_cvt_pk_bf16_f32 v79, v207, v208
	v_cvt_pk_bf16_f32 v80, v209, v210
	v_cvt_pk_bf16_f32 v81, v211, v197
	v_fmac_f32_e32 v212, v196, v0
	v_permlane32_swap_b32_e32 v66, v68
	v_permlane32_swap_b32_e32 v67, v69
	v_permlane32_swap_b32_e32 v70, v72
	v_permlane32_swap_b32_e32 v71, v73
	v_permlane32_swap_b32_e32 v74, v76
	v_permlane32_swap_b32_e32 v75, v77
	v_permlane32_swap_b32_e32 v78, v80
	v_permlane32_swap_b32_e32 v79, v81
	v_add_u32_e32 v0, s55, v193
	ds_read_b64_tr_b16 v[82:83], v0 offset:0
	ds_read_b64_tr_b16 v[84:85], v0 offset:0x800
	ds_read_b64_tr_b16 v[86:87], v0 offset:0x1000
	ds_read_b64_tr_b16 v[88:89], v0 offset:0x1800
	ds_read_b64_tr_b16 v[90:91], v0 offset:0x2000
	ds_read_b64_tr_b16 v[92:93], v0 offset:0x2800
	ds_read_b64_tr_b16 v[94:95], v0 offset:0x3000
	ds_read_b64_tr_b16 v[96:97], v0 offset:0x3800
	s_waitcnt lgkmcnt(0)
	s_nop 0
	v_mfma_f32_32x32x16_bf16 v[50:65], v[66:69], v[82:85], v[50:65]
	ds_read_b64_tr_b16 v[82:83], v0 offset:0x200
	ds_read_b64_tr_b16 v[84:85], v0 offset:0xa00
	v_mfma_f32_32x32x16_bf16 v[50:65], v[70:73], v[86:89], v[50:65]
	ds_read_b64_tr_b16 v[86:87], v0 offset:0x1200
	ds_read_b64_tr_b16 v[88:89], v0 offset:0x1a00
	v_mfma_f32_32x32x16_bf16 v[50:65], v[74:77], v[90:93], v[50:65]
	ds_read_b64_tr_b16 v[90:91], v0 offset:0x2200
	ds_read_b64_tr_b16 v[92:93], v0 offset:0x2a00
	ds_read_b64_tr_b16 v[196:197], v0 offset:0x3200
	ds_read_b64_tr_b16 v[198:199], v0 offset:0x3a00
	s_waitcnt lgkmcnt(0)
	v_mfma_f32_32x32x16_bf16 v[50:65], v[78:81], v[94:97], v[50:65]
	v_mfma_f32_32x32x16_bf16 v[34:49], v[66:69], v[82:85], v[34:49]
	s_andn2_b64 vcc, exec, s[30:31]
	s_cbranch_vccnz .Lmla_nostage
	s_xor_b32 s6, s54, 1
	s_lshl_b32 s7, s6, 14
	v_add_u32_e32 v202, s7, v182
	s_waitcnt vmcnt(4)
	ds_write_b128 v202, v[98:101]
	v_add_u32_e32 v203, s7, v181
	s_waitcnt vmcnt(3)
	ds_write_b128 v203, v[102:105]
	v_add_u32_e32 v204, s7, v184
	s_mulk_i32 s6, 0x2400
	s_waitcnt vmcnt(2)
	ds_write_b128 v204, v[106:109] offset:32768
	s_waitcnt vmcnt(1)
	ds_write_b128 v204, v[110:113] offset:40960
	v_add_u32_e32 v205, s6, v185
	s_waitcnt vmcnt(0)
	ds_write_b128 v205, v[130:133]
	s_mov_b64 s[30:31], 0
; template <int VB, bool SK>
; __device__ __forceinline__ void pv_tile(f32x16* o, int vb0, bf16x8 pa0, bf16x8 pa1, bf16x8 pa2, bf16x8 pa3, bool act) {
;     ...
;     PV_D0(0); PV_D0(1); PV_D0(2); PV_D0(3);
.Lmla_nostage:
	ds_read_b64_tr_b16 v[82:83], v0 offset:0x400
	ds_read_b64_tr_b16 v[84:85], v0 offset:0xc00
	v_mfma_f32_32x32x16_bf16 v[34:49], v[70:73], v[86:89], v[34:49]
	ds_read_b64_tr_b16 v[86:87], v0 offset:0x1400
	ds_read_b64_tr_b16 v[88:89], v0 offset:0x1c00
	v_mfma_f32_32x32x16_bf16 v[34:49], v[74:77], v[90:93], v[34:49]
	ds_read_b64_tr_b16 v[90:91], v0 offset:0x2400
	ds_read_b64_tr_b16 v[92:93], v0 offset:0x2c00
	ds_read_b64_tr_b16 v[94:95], v0 offset:0x3400
	ds_read_b64_tr_b16 v[96:97], v0 offset:0x3c00
	s_waitcnt lgkmcnt(0)
	v_mfma_f32_32x32x16_bf16 v[34:49], v[78:81], v[196:199], v[34:49]
	v_mfma_f32_32x32x16_bf16 v[18:33], v[66:69], v[82:85], v[18:33]
	ds_read_b64_tr_b16 v[82:83], v0 offset:0x600
	ds_read_b64_tr_b16 v[84:85], v0 offset:0xe00
	v_mfma_f32_32x32x16_bf16 v[18:33], v[70:73], v[86:89], v[18:33]
	ds_read_b64_tr_b16 v[86:87], v0 offset:0x1600
	ds_read_b64_tr_b16 v[88:89], v0 offset:0x1e00
	v_mfma_f32_32x32x16_bf16 v[18:33], v[74:77], v[90:93], v[18:33]
	ds_read_b64_tr_b16 v[90:91], v0 offset:0x2600
	ds_read_b64_tr_b16 v[92:93], v0 offset:0x2e00
	ds_read_b64_tr_b16 v[198:199], v0 offset:0x3600
	ds_read_b64_tr_b16 v[200:201], v0 offset:0x3e00
	s_waitcnt lgkmcnt(0)
	v_mfma_f32_32x32x16_bf16 v[18:33], v[78:81], v[94:97], v[18:33]
	v_mfma_f32_32x32x16_bf16 v[2:17], v[66:69], v[82:85], v[2:17]
	v_mov_b32_e32 v196, v212
	v_mfma_f32_32x32x16_bf16 v[2:17], v[70:73], v[86:89], v[2:17]
	v_mfma_f32_32x32x16_bf16 v[2:17], v[74:77], v[90:93], v[2:17]
	v_mfma_f32_32x32x16_bf16 v[2:17], v[78:81], v[198:201], v[2:17]

; __device__ __forceinline__ int crow(int r, int hi) { return (r & 3) + 8 * (r >> 2) + 4 * hi; }
; __device__ __forceinline__ void mla_block(const MlaRef& cur, char* lds) {
;     ...
;     if (hi == 0) li_l[r32] = l_reg; asm volatile("s_waitcnt lgkmcnt(0)" ::: "memory");
;     float rli[16];
; #pragma unroll
;     for (int r = 0; r < 16; ++r) rli[r] = __builtin_amdgcn_rcpf(li_l[crow(r, hi)]);
;     bf16* Ow = cur.O + (size_t)(wid * QBLK) * MLA_OS;
; #pragma unroll
;     for (int r = 0; r < 16; ++r) { const int orow = crow(r, hi);
; #pragma unroll
;         for (int d0 = 0; d0 < 4; ++d0) { const float v = o[d0][r] * rli[r];
;             const float vn = __shfl_xor(v, 1);
;             if ((r32 & 1) == 0) *(unsigned*)(Ow + (size_t)orow * MLA_OS + d0 * 32 + r32) = cvtpk(v, vn); } }
.LBB0_850:
	s_and_saveexec_b64 s[6:7], s[4:5]
	ds_write_b32 v187, v196
	s_or_b64 exec, exec, s[6:7]
	s_waitcnt lgkmcnt(0)
	ds_read_b128 v[78:81], v183
	ds_read_b128 v[74:77], v183 offset:32
	ds_read_b128 v[70:73], v183 offset:64
	ds_read_b128 v[66:69], v183 offset:96
	s_or_b32 s4, s25, s47
	s_ashr_i32 s5, s4, 31
	s_lshl_b64 s[4:5], s[4:5], 11
	s_add_u32 s4, s26, s4
	s_addc_u32 s5, s27, s5
	s_add_u32 s6, s4, s48
	s_addc_u32 s7, s5, 0
	s_ashr_i32 s25, s24, 31
	s_lshl_b64 s[4:5], s[24:25], 11
	s_add_u32 s6, s6, s4
	s_addc_u32 s7, s7, s5
	s_add_u32 s28, s6, s12
	s_addc_u32 s29, s7, s13
	v_lshlrev_b32_e32 v82, 1, v177
	v_lshl_add_u32 v82, v176, 13, v82
	v_mov_b32_e32 v88, v82
	v_add_u32_e32 v89, 0x1000, v82
	v_add_u32_e32 v90, 0x4000, v82
	v_add_u32_e32 v91, 0x5000, v82
	v_add_u32_e32 v92, 0x8000, v82
	v_add_u32_e32 v93, 0x9000, v82
	v_add_u32_e32 v94, 0xc000, v82
	v_add_u32_e32 v95, 0xd000, v82
	v_and_b32_e32 v0, 1, v175
	v_cmp_eq_u32_e64 s[4:5], 0, v0
	s_waitcnt lgkmcnt(0)
	v_rcp_f32_e32 v78, v78
	v_rcp_f32_e32 v79, v79
	v_rcp_f32_e32 v80, v80
	v_rcp_f32_e32 v81, v81
	v_rcp_f32_e32 v74, v74
	v_rcp_f32_e32 v75, v75
	v_rcp_f32_e32 v76, v76
	v_rcp_f32_e32 v77, v77
	v_rcp_f32_e32 v70, v70
	v_rcp_f32_e32 v71, v71
	v_rcp_f32_e32 v72, v72
	v_rcp_f32_e32 v73, v73
	v_rcp_f32_e32 v66, v66
	v_rcp_f32_e32 v67, v67
	v_rcp_f32_e32 v68, v68
	v_rcp_f32_e32 v69, v69
	v_mul_f32_e32 v50, v50, v78
	v_mul_f32_e32 v34, v34, v78
	v_mul_f32_e32 v18, v18, v78
	v_mul_f32_e32 v2, v2, v78
	v_mul_f32_e32 v51, v51, v79
	v_mul_f32_e32 v35, v35, v79
	v_mul_f32_e32 v19, v19, v79
	v_mul_f32_e32 v3, v3, v79
	v_mul_f32_e32 v52, v52, v80
	v_mul_f32_e32 v36, v36, v80
	v_mul_f32_e32 v20, v20, v80
	v_mul_f32_e32 v4, v4, v80
	v_mul_f32_e32 v53, v53, v81
	v_mul_f32_e32 v37, v37, v81
	v_mul_f32_e32 v21, v21, v81
	v_mul_f32_e32 v5, v5, v81
	v_mul_f32_e32 v54, v54, v74
	v_mul_f32_e32 v38, v38, v74
	v_mul_f32_e32 v22, v22, v74
	v_mul_f32_e32 v6, v6, v74
	v_mul_f32_e32 v55, v55, v75
	v_mul_f32_e32 v39, v39, v75
	v_mul_f32_e32 v23, v23, v75
	v_mul_f32_e32 v7, v7, v75
	v_mul_f32_e32 v56, v56, v76
	v_mul_f32_e32 v40, v40, v76
	v_mul_f32_e32 v24, v24, v76
	v_mul_f32_e32 v8, v8, v76
	v_mul_f32_e32 v57, v57, v77
	v_mul_f32_e32 v41, v41, v77
	v_mul_f32_e32 v25, v25, v77
	v_mul_f32_e32 v9, v9, v77
	v_mul_f32_e32 v58, v58, v70
	v_mul_f32_e32 v42, v42, v70
	v_mul_f32_e32 v26, v26, v70
	v_mul_f32_e32 v10, v10, v70
	v_mul_f32_e32 v59, v59, v71
	v_mul_f32_e32 v43, v43, v71
	v_mul_f32_e32 v27, v27, v71
	v_mul_f32_e32 v11, v11, v71
	v_mul_f32_e32 v60, v60, v72
	v_mul_f32_e32 v44, v44, v72
	v_mul_f32_e32 v28, v28, v72
	v_mul_f32_e32 v12, v12, v72
	v_mul_f32_e32 v61, v61, v73
	v_mul_f32_e32 v45, v45, v73
	v_mul_f32_e32 v29, v29, v73
	v_mul_f32_e32 v13, v13, v73
	v_mul_f32_e32 v62, v62, v66
	v_mul_f32_e32 v46, v46, v66
	v_mul_f32_e32 v30, v30, v66
	v_mul_f32_e32 v14, v14, v66
	v_mul_f32_e32 v63, v63, v67
	v_mul_f32_e32 v47, v47, v67
	v_mul_f32_e32 v31, v31, v67
	v_mul_f32_e32 v15, v15, v67
	v_mul_f32_e32 v64, v64, v68
	v_mul_f32_e32 v48, v48, v68
	v_mul_f32_e32 v32, v32, v68
	v_mul_f32_e32 v16, v16, v68
	v_mul_f32_e32 v65, v65, v69
	v_mul_f32_e32 v49, v49, v69
	v_mul_f32_e32 v33, v33, v69
	v_mul_f32_e32 v17, v17, v69
	v_mov_b32_dpp v84, v50 quad_perm:[1,0,3,2] row_mask:0xf bank_mask:0xf
	v_cvt_pk_bf16_f32 v50, v50, v84
	v_mov_b32_dpp v85, v34 quad_perm:[1,0,3,2] row_mask:0xf bank_mask:0xf
	v_cvt_pk_bf16_f32 v34, v34, v85
	v_mov_b32_dpp v86, v18 quad_perm:[1,0,3,2] row_mask:0xf bank_mask:0xf
	v_cvt_pk_bf16_f32 v18, v18, v86
	v_mov_b32_dpp v87, v2 quad_perm:[1,0,3,2] row_mask:0xf bank_mask:0xf
	v_cvt_pk_bf16_f32 v2, v2, v87
	v_mov_b32_dpp v84, v51 quad_perm:[1,0,3,2] row_mask:0xf bank_mask:0xf
	v_cvt_pk_bf16_f32 v51, v51, v84
	v_mov_b32_dpp v85, v35 quad_perm:[1,0,3,2] row_mask:0xf bank_mask:0xf
	v_cvt_pk_bf16_f32 v35, v35, v85
	v_mov_b32_dpp v86, v19 quad_perm:[1,0,3,2] row_mask:0xf bank_mask:0xf
	v_cvt_pk_bf16_f32 v19, v19, v86
	v_mov_b32_dpp v87, v3 quad_perm:[1,0,3,2] row_mask:0xf bank_mask:0xf
	v_cvt_pk_bf16_f32 v3, v3, v87
	v_mov_b32_dpp v84, v52 quad_perm:[1,0,3,2] row_mask:0xf bank_mask:0xf
	v_cvt_pk_bf16_f32 v52, v52, v84
	v_mov_b32_dpp v85, v36 quad_perm:[1,0,3,2] row_mask:0xf bank_mask:0xf
	v_cvt_pk_bf16_f32 v36, v36, v85
	v_mov_b32_dpp v86, v20 quad_perm:[1,0,3,2] row_mask:0xf bank_mask:0xf
	v_cvt_pk_bf16_f32 v20, v20, v86
	v_mov_b32_dpp v87, v4 quad_perm:[1,0,3,2] row_mask:0xf bank_mask:0xf
	v_cvt_pk_bf16_f32 v4, v4, v87
	v_mov_b32_dpp v84, v53 quad_perm:[1,0,3,2] row_mask:0xf bank_mask:0xf
	v_cvt_pk_bf16_f32 v53, v53, v84
	v_mov_b32_dpp v85, v37 quad_perm:[1,0,3,2] row_mask:0xf bank_mask:0xf
	v_cvt_pk_bf16_f32 v37, v37, v85
	v_mov_b32_dpp v86, v21 quad_perm:[1,0,3,2] row_mask:0xf bank_mask:0xf
	v_cvt_pk_bf16_f32 v21, v21, v86
	v_mov_b32_dpp v87, v5 quad_perm:[1,0,3,2] row_mask:0xf bank_mask:0xf
	v_cvt_pk_bf16_f32 v5, v5, v87
	v_mov_b32_dpp v84, v54 quad_perm:[1,0,3,2] row_mask:0xf bank_mask:0xf
	v_cvt_pk_bf16_f32 v54, v54, v84
	v_mov_b32_dpp v85, v38 quad_perm:[1,0,3,2] row_mask:0xf bank_mask:0xf
	v_cvt_pk_bf16_f32 v38, v38, v85
	v_mov_b32_dpp v86, v22 quad_perm:[1,0,3,2] row_mask:0xf bank_mask:0xf
	v_cvt_pk_bf16_f32 v22, v22, v86
	v_mov_b32_dpp v87, v6 quad_perm:[1,0,3,2] row_mask:0xf bank_mask:0xf
	v_cvt_pk_bf16_f32 v6, v6, v87
	v_mov_b32_dpp v84, v55 quad_perm:[1,0,3,2] row_mask:0xf bank_mask:0xf
	v_cvt_pk_bf16_f32 v55, v55, v84
	v_mov_b32_dpp v85, v39 quad_perm:[1,0,3,2] row_mask:0xf bank_mask:0xf
	v_cvt_pk_bf16_f32 v39, v39, v85
	v_mov_b32_dpp v86, v23 quad_perm:[1,0,3,2] row_mask:0xf bank_mask:0xf
	v_cvt_pk_bf16_f32 v23, v23, v86
	v_mov_b32_dpp v87, v7 quad_perm:[1,0,3,2] row_mask:0xf bank_mask:0xf
; __device__ __forceinline__ int crow(int r, int hi) { return (r & 3) + 8 * (r >> 2) + 4 * hi; }
; __device__ __forceinline__ void mla_block(const MlaRef& cur, char* lds) {
;     ...
;     for (int r = 0; r < 16; ++r) { const int orow = crow(r, hi);
; #pragma unroll
;         for (int d0 = 0; d0 < 4; ++d0) { const float v = o[d0][r] * rli[r];
;             const float vn = __shfl_xor(v, 1);
;             if ((r32 & 1) == 0) *(unsigned*)(Ow + (size_t)orow * MLA_OS + d0 * 32 + r32) = cvtpk(v, vn); } }
	v_cvt_pk_bf16_f32 v7, v7, v87
	v_mov_b32_dpp v84, v56 quad_perm:[1,0,3,2] row_mask:0xf bank_mask:0xf
	v_cvt_pk_bf16_f32 v56, v56, v84
	v_mov_b32_dpp v85, v40 quad_perm:[1,0,3,2] row_mask:0xf bank_mask:0xf
	v_cvt_pk_bf16_f32 v40, v40, v85
	v_mov_b32_dpp v86, v24 quad_perm:[1,0,3,2] row_mask:0xf bank_mask:0xf
	v_cvt_pk_bf16_f32 v24, v24, v86
	v_mov_b32_dpp v87, v8 quad_perm:[1,0,3,2] row_mask:0xf bank_mask:0xf
	v_cvt_pk_bf16_f32 v8, v8, v87
	v_mov_b32_dpp v84, v57 quad_perm:[1,0,3,2] row_mask:0xf bank_mask:0xf
	v_cvt_pk_bf16_f32 v57, v57, v84
	v_mov_b32_dpp v85, v41 quad_perm:[1,0,3,2] row_mask:0xf bank_mask:0xf
	v_cvt_pk_bf16_f32 v41, v41, v85
	v_mov_b32_dpp v86, v25 quad_perm:[1,0,3,2] row_mask:0xf bank_mask:0xf
	v_cvt_pk_bf16_f32 v25, v25, v86
	v_mov_b32_dpp v87, v9 quad_perm:[1,0,3,2] row_mask:0xf bank_mask:0xf
	v_cvt_pk_bf16_f32 v9, v9, v87
	v_mov_b32_dpp v84, v58 quad_perm:[1,0,3,2] row_mask:0xf bank_mask:0xf
	v_cvt_pk_bf16_f32 v58, v58, v84
	v_mov_b32_dpp v85, v42 quad_perm:[1,0,3,2] row_mask:0xf bank_mask:0xf
	v_cvt_pk_bf16_f32 v42, v42, v85
	v_mov_b32_dpp v86, v26 quad_perm:[1,0,3,2] row_mask:0xf bank_mask:0xf
	v_cvt_pk_bf16_f32 v26, v26, v86
	v_mov_b32_dpp v87, v10 quad_perm:[1,0,3,2] row_mask:0xf bank_mask:0xf
	v_cvt_pk_bf16_f32 v10, v10, v87
	v_mov_b32_dpp v84, v59 quad_perm:[1,0,3,2] row_mask:0xf bank_mask:0xf
	v_cvt_pk_bf16_f32 v59, v59, v84
	v_mov_b32_dpp v85, v43 quad_perm:[1,0,3,2] row_mask:0xf bank_mask:0xf
	v_cvt_pk_bf16_f32 v43, v43, v85
	v_mov_b32_dpp v86, v27 quad_perm:[1,0,3,2] row_mask:0xf bank_mask:0xf
	v_cvt_pk_bf16_f32 v27, v27, v86
	v_mov_b32_dpp v87, v11 quad_perm:[1,0,3,2] row_mask:0xf bank_mask:0xf
	v_cvt_pk_bf16_f32 v11, v11, v87
	v_mov_b32_dpp v84, v60 quad_perm:[1,0,3,2] row_mask:0xf bank_mask:0xf
	v_cvt_pk_bf16_f32 v60, v60, v84
	v_mov_b32_dpp v85, v44 quad_perm:[1,0,3,2] row_mask:0xf bank_mask:0xf
	v_cvt_pk_bf16_f32 v44, v44, v85
	v_mov_b32_dpp v86, v28 quad_perm:[1,0,3,2] row_mask:0xf bank_mask:0xf
	v_cvt_pk_bf16_f32 v28, v28, v86
	v_mov_b32_dpp v87, v12 quad_perm:[1,0,3,2] row_mask:0xf bank_mask:0xf
	v_cvt_pk_bf16_f32 v12, v12, v87
	v_mov_b32_dpp v84, v61 quad_perm:[1,0,3,2] row_mask:0xf bank_mask:0xf
	v_cvt_pk_bf16_f32 v61, v61, v84
	v_mov_b32_dpp v85, v45 quad_perm:[1,0,3,2] row_mask:0xf bank_mask:0xf
	v_cvt_pk_bf16_f32 v45, v45, v85
	v_mov_b32_dpp v86, v29 quad_perm:[1,0,3,2] row_mask:0xf bank_mask:0xf
	v_cvt_pk_bf16_f32 v29, v29, v86
	v_mov_b32_dpp v87, v13 quad_perm:[1,0,3,2] row_mask:0xf bank_mask:0xf
	v_cvt_pk_bf16_f32 v13, v13, v87
	v_mov_b32_dpp v84, v62 quad_perm:[1,0,3,2] row_mask:0xf bank_mask:0xf
	v_cvt_pk_bf16_f32 v62, v62, v84
	v_mov_b32_dpp v85, v46 quad_perm:[1,0,3,2] row_mask:0xf bank_mask:0xf
	v_cvt_pk_bf16_f32 v46, v46, v85
	v_mov_b32_dpp v86, v30 quad_perm:[1,0,3,2] row_mask:0xf bank_mask:0xf
	v_cvt_pk_bf16_f32 v30, v30, v86
	v_mov_b32_dpp v87, v14 quad_perm:[1,0,3,2] row_mask:0xf bank_mask:0xf
	v_cvt_pk_bf16_f32 v14, v14, v87
	v_mov_b32_dpp v84, v63 quad_perm:[1,0,3,2] row_mask:0xf bank_mask:0xf
	v_cvt_pk_bf16_f32 v63, v63, v84
	v_mov_b32_dpp v85, v47 quad_perm:[1,0,3,2] row_mask:0xf bank_mask:0xf
	v_cvt_pk_bf16_f32 v47, v47, v85
	v_mov_b32_dpp v86, v31 quad_perm:[1,0,3,2] row_mask:0xf bank_mask:0xf
	v_cvt_pk_bf16_f32 v31, v31, v86
	v_mov_b32_dpp v87, v15 quad_perm:[1,0,3,2] row_mask:0xf bank_mask:0xf
	v_cvt_pk_bf16_f32 v15, v15, v87
	v_mov_b32_dpp v84, v64 quad_perm:[1,0,3,2] row_mask:0xf bank_mask:0xf
	v_cvt_pk_bf16_f32 v64, v64, v84
	v_mov_b32_dpp v85, v48 quad_perm:[1,0,3,2] row_mask:0xf bank_mask:0xf
	v_cvt_pk_bf16_f32 v48, v48, v85
	v_mov_b32_dpp v86, v32 quad_perm:[1,0,3,2] row_mask:0xf bank_mask:0xf
	v_cvt_pk_bf16_f32 v32, v32, v86
; __device__ __forceinline__ int crow(int r, int hi) { return (r & 3) + 8 * (r >> 2) + 4 * hi; }
; __device__ __forceinline__ void mla_block(const MlaRef& cur, char* lds) {
;     ...
;     for (int r = 0; r < 16; ++r) { const int orow = crow(r, hi);
; #pragma unroll
;         for (int d0 = 0; d0 < 4; ++d0) { const float v = o[d0][r] * rli[r];
;             const float vn = __shfl_xor(v, 1);
;             if ((r32 & 1) == 0) *(unsigned*)(Ow + (size_t)orow * MLA_OS + d0 * 32 + r32) = cvtpk(v, vn); } }
	v_mov_b32_dpp v87, v16 quad_perm:[1,0,3,2] row_mask:0xf bank_mask:0xf
	v_cvt_pk_bf16_f32 v16, v16, v87
	v_mov_b32_dpp v84, v65 quad_perm:[1,0,3,2] row_mask:0xf bank_mask:0xf
	v_cvt_pk_bf16_f32 v65, v65, v84
	v_mov_b32_dpp v85, v49 quad_perm:[1,0,3,2] row_mask:0xf bank_mask:0xf
	v_cvt_pk_bf16_f32 v49, v49, v85
	v_mov_b32_dpp v86, v33 quad_perm:[1,0,3,2] row_mask:0xf bank_mask:0xf
	v_cvt_pk_bf16_f32 v33, v33, v86
	v_mov_b32_dpp v87, v17 quad_perm:[1,0,3,2] row_mask:0xf bank_mask:0xf
	v_cvt_pk_bf16_f32 v17, v17, v87
	s_and_saveexec_b64 s[6:7], s[4:5]
	global_store_dword v88, v50, s[28:29]
	global_store_dword v88, v34, s[28:29] offset:64
	global_store_dword v88, v18, s[28:29] offset:128
	global_store_dword v88, v2, s[28:29] offset:192
	global_store_dword v88, v51, s[28:29] offset:2048
	global_store_dword v88, v35, s[28:29] offset:2112
	global_store_dword v88, v19, s[28:29] offset:2176
	global_store_dword v88, v3, s[28:29] offset:2240
	global_store_dword v89, v52, s[28:29]
	global_store_dword v89, v36, s[28:29] offset:64
	global_store_dword v89, v20, s[28:29] offset:128
	global_store_dword v89, v4, s[28:29] offset:192
	global_store_dword v89, v53, s[28:29] offset:2048
	global_store_dword v89, v37, s[28:29] offset:2112
	global_store_dword v89, v21, s[28:29] offset:2176
	global_store_dword v89, v5, s[28:29] offset:2240
	global_store_dword v90, v54, s[28:29]
	global_store_dword v90, v38, s[28:29] offset:64
	global_store_dword v90, v22, s[28:29] offset:128
	global_store_dword v90, v6, s[28:29] offset:192
	global_store_dword v90, v55, s[28:29] offset:2048
	global_store_dword v90, v39, s[28:29] offset:2112
	global_store_dword v90, v23, s[28:29] offset:2176
	global_store_dword v90, v7, s[28:29] offset:2240
	global_store_dword v91, v56, s[28:29]
	global_store_dword v91, v40, s[28:29] offset:64
	global_store_dword v91, v24, s[28:29] offset:128
	global_store_dword v91, v8, s[28:29] offset:192
	global_store_dword v91, v57, s[28:29] offset:2048
	global_store_dword v91, v41, s[28:29] offset:2112
	global_store_dword v91, v25, s[28:29] offset:2176
	global_store_dword v91, v9, s[28:29] offset:2240
	global_store_dword v92, v58, s[28:29]
	global_store_dword v92, v42, s[28:29] offset:64
	global_store_dword v92, v26, s[28:29] offset:128
	global_store_dword v92, v10, s[28:29] offset:192
	global_store_dword v92, v59, s[28:29] offset:2048
	global_store_dword v92, v43, s[28:29] offset:2112
	global_store_dword v92, v27, s[28:29] offset:2176
	global_store_dword v92, v11, s[28:29] offset:2240
	global_store_dword v93, v60, s[28:29]
	global_store_dword v93, v44, s[28:29] offset:64
	global_store_dword v93, v28, s[28:29] offset:128
	global_store_dword v93, v12, s[28:29] offset:192
	global_store_dword v93, v61, s[28:29] offset:2048
	global_store_dword v93, v45, s[28:29] offset:2112
	global_store_dword v93, v29, s[28:29] offset:2176
	global_store_dword v93, v13, s[28:29] offset:2240
	global_store_dword v94, v62, s[28:29]
	global_store_dword v94, v46, s[28:29] offset:64
	global_store_dword v94, v30, s[28:29] offset:128
	global_store_dword v94, v14, s[28:29] offset:192
	global_store_dword v94, v63, s[28:29] offset:2048
	global_store_dword v94, v47, s[28:29] offset:2112
	global_store_dword v94, v31, s[28:29] offset:2176
	global_store_dword v94, v15, s[28:29] offset:2240
	global_store_dword v95, v64, s[28:29]
	global_store_dword v95, v48, s[28:29] offset:64
	global_store_dword v95, v32, s[28:29] offset:128
	global_store_dword v95, v16, s[28:29] offset:192
	global_store_dword v95, v65, s[28:29] offset:2048
	global_store_dword v95, v49, s[28:29] offset:2112
	global_store_dword v95, v33, s[28:29] offset:2176
	global_store_dword v95, v17, s[28:29] offset:2240
	s_branch .LBB0_835
